# rstd row-scale loads of the in-proj and FFN-up GEMM epilogues hoisted to the top of each tile's unit loop (into v242-249, free in those loops): the epilogue no longer drains vmcnt(0) behind the next t
# speedup vs baseline: 1.0090x; 1.0039x over previous
;     __host__ __device__ bool next(int i, Unit& u) const {
;         const long L = (long)i * G + c; if (L >= nwg) return false;
;         int wgid = (int)L; { const int q = nwg / NXCD, r = nwg % NXCD, xcd = wgid % NXCD, off = wgid / NXCD; wgid = (xcd < r ? xcd * (q + 1) : r * (q + 1) + (xcd - r) * q) + off; }
;         const int nig = WGM * nN, gid = wgid / nig, fm = gid * WGM, gsz = (nM - fm) < WGM ? (nM - fm) : WGM;
;         u.pm = fm + ((wgid % nig) % gsz); u.pn = (wgid % nig) / gsz; return true;
;     __device__ __forceinline__ void operator()(const f32x4 (&acc)[2][2][4][2], const Unit& u, int wr, int wc, int fr, int fq) const {
;     ...
;         { const f32x4 r0 = *(const f32x4*)(rstd + u.pm * BM + (wr * 16 + fr) * 8), r1 = *(const f32x4*)(rstd + u.pm * BM + (wr * 16 + fr) * 8 + 4);
.LBB0_298:
	s_lshl_b32 s4, s22, 8
	s_ashr_i32 s5, s4, 31
	v_lshl_add_u64 v[242:243], s[4:5], 2, v[146:147]
	global_load_dwordx4 v[246:249], v[242:243], off offset:16
	s_nop 0
	global_load_dwordx4 v[242:245], v[242:243], off
	s_add_i32 s43, s43, 1
	s_mul_i32 s4, s43, s42
	s_mul_hi_u32 s5, s43, s30
	s_add_i32 s5, s5, s4
	s_mul_i32 s4, s43, s30
	s_add_u32 s16, s4, s31
	s_addc_u32 s17, s5, s36
	v_mov_b64_e32 v[2:3], 0x580
	v_cmp_lt_i64_e64 s[4:5], s[16:17], v[2:3]
	v_mov_b64_e32 v[2:3], 0x57f
	v_cmp_gt_i64_e32 vcc, s[16:17], v[2:3]
	s_cbranch_vccnz .LBB0_300
	s_ashr_i32 s10, s16, 31
	s_lshr_b32 s10, s10, 29
	s_add_i32 s10, s16, s10
	s_ashr_i32 s11, s10, 3
	s_and_b32 s10, s10, -8
	s_sub_i32 s10, s16, s10
	s_cmp_lt_i32 s10, 0
	s_cselect_b32 s12, s51, 0xb0
	s_mul_i32 s10, s10, s12
	s_add_i32 s10, s10, s11
	s_mul_hi_i32 s11, s10, 0x2e8ba2e9
	s_lshr_b32 s12, s11, 31
	s_ashr_i32 s11, s11, 4
	s_add_i32 s11, s11, s12
	s_lshl_b32 s12, s11, 3
	s_sub_i32 s13, 0x80, s12
	s_min_i32 s13, s13, 8
	s_abs_i32 s16, s13
	v_cvt_f32_u32_e32 v2, s16
	s_sub_i32 s18, 0, s16
	s_mulk_i32 s11, 0x58
	s_sub_i32 s11, s10, s11
	v_rcp_iflag_f32_e32 v2, v2
	s_abs_i32 s10, s11
	s_xor_b32 s17, s11, s13
	s_ashr_i32 s17, s17, 31
	v_mul_f32_e32 v2, 0x4f7ffffe, v2
	v_cvt_u32_f32_e32 v2, v2
	s_nop 0
	v_readfirstlane_b32 s19, v2
	s_mul_i32 s18, s18, s19
	s_mul_hi_u32 s18, s19, s18
	s_add_i32 s19, s19, s18
	s_mul_hi_u32 s18, s10, s19
	s_mul_i32 s19, s18, s16
	s_sub_i32 s10, s10, s19
	s_add_i32 s21, s18, 1
	s_sub_i32 s19, s10, s16
	s_cmp_ge_u32 s10, s16
	s_cselect_b32 s18, s21, s18
	s_cselect_b32 s10, s19, s10
	s_add_i32 s19, s18, 1
	s_cmp_ge_u32 s10, s16
	s_cselect_b32 s10, s19, s18
	s_xor_b32 s10, s10, s17
	s_sub_i32 s10, s10, s17
	s_mul_i32 s13, s10, s13
	s_sub_i32 s11, s11, s13
	s_add_i32 s12, s12, s11

; __device__ __forceinline__ unsigned cvt_pk_bf16(float lo, float hi) { unsigned r; asm volatile("v_cvt_pk_bf16_f32 %0, %1, %2" : "=v"(r) : "v"(lo), "v"(hi)); return r; }
;     __device__ __forceinline__ void operator()(const f32x4 (&acc)[2][2][4][2], const Unit& u, int wr, int wc, int fr, int fq) const {
;         const int row0 = u.pm * BM + wr * 64 + fr; const int col0 = wc * 32 + 8 * fq;
;         float rs[2][4];
;         { const f32x4 r0 = *(const f32x4*)(rstd + u.pm * BM + (wr * 16 + fr) * 8), r1 = *(const f32x4*)(rstd + u.pm * BM + (wr * 16 + fr) * 8 + 4);
; #pragma unroll
;           for (int m = 0; m < 4; ++m) { rs[0][m] = r0[m]; rs[1][m] = r1[m]; } }
; #pragma unroll
;         for (int ai = 0; ai < 2; ++ai)
; #pragma unroll
;             for (int m = 0; m < 4; ++m) { const int row = row0 + ai * HALF + m * 16; const float r = rs[ai][m];
; #pragma unroll
;                 for (int bj = 0; bj < 2; ++bj) { const f32x4 v0 = acc[ai][bj][m][0] * r, v1 = acc[ai][bj][m][1] * r;
;                     u32x4 w; w.x = cvt_pk_bf16(v0[0], v0[1]); w.y = cvt_pk_bf16(v0[2], v0[3]); w.z = cvt_pk_bf16(v1[0], v1[1]); w.w = cvt_pk_bf16(v1[2], v1[3]);
;                     *(u32x4*)(O + ((size_t)u.pn * Mrows + row) * 256 + bj * HALF + col0) = w; } }
;     }
.LBB0_304:
	s_lshl_b32 s24, s22, 8
	s_ashr_i32 s25, s24, 31
	v_mov_b64_e32 v[94:95], v[246:247]
	v_mov_b64_e32 v[96:97], v[248:249]
	v_mov_b64_e32 v[134:135], v[242:243]
	v_mov_b64_e32 v[136:137], v[244:245]
	v_add_u32_e32 v154, s24, v1
	s_ashr_i32 s21, s20, 31
	v_ashrrev_i32_e32 v155, 31, v154
	s_lshl_b64 s[20:21], s[20:21], 15
	s_andn2_b64 vcc, exec, s[4:5]
	v_pk_mul_f32 v[62:63], v[62:63], v[94:95] op_sel_hi:[1,0]
	v_pk_mul_f32 v[130:131], v[130:131], v[134:135] op_sel_hi:[1,0]
	v_pk_mul_f32 v[158:159], v[128:129], v[134:135] op_sel_hi:[1,0]
	v_pk_mul_f32 v[128:129], v[126:127], v[134:135] op_sel_hi:[1,0]
	v_cvt_pk_bf16_f32 v126, v130, v131
	v_lshl_add_u64 v[130:131], s[20:21], 0, v[154:155]
	v_lshlrev_b64 v[130:131], 9, v[130:131]
	v_pk_mul_f32 v[132:133], v[132:133], v[134:135] op_sel_hi:[1,0]
	v_lshl_add_u64 v[130:131], v[148:149], 0, v[130:131]
	v_cvt_pk_bf16_f32 v127, v132, v133
	v_cvt_pk_bf16_f32 v128, v128, v129
	v_cvt_pk_bf16_f32 v129, v158, v159
	global_store_dwordx4 v[130:131], v[126:129], off
	v_pk_mul_f32 v[122:123], v[122:123], v[134:135] op_sel_hi:[1,0]
	v_pk_mul_f32 v[124:125], v[124:125], v[134:135] op_sel_hi:[1,0]
	v_pk_mul_f32 v[126:127], v[120:121], v[134:135] op_sel_hi:[1,0]
	v_pk_mul_f32 v[120:121], v[118:119], v[134:135] op_sel_hi:[1,0]
	v_cvt_pk_bf16_f32 v118, v122, v123
	v_cvt_pk_bf16_f32 v119, v124, v125
	v_pk_mul_f32 v[114:115], v[114:115], v[134:135] op_sel:[0,1]
	v_cvt_pk_bf16_f32 v120, v120, v121
	v_cvt_pk_bf16_f32 v121, v126, v127
	global_store_dwordx4 v[130:131], v[118:121], off offset:256
	v_pk_mul_f32 v[116:117], v[116:117], v[134:135] op_sel:[0,1]
	v_pk_mul_f32 v[106:107], v[106:107], v[134:135] op_sel:[0,1]
	v_or_b32_e32 v118, 16, v154
	v_ashrrev_i32_e32 v119, 31, v118
	v_pk_mul_f32 v[120:121], v[112:113], v[134:135] op_sel:[0,1]
	v_pk_mul_f32 v[112:113], v[110:111], v[134:135] op_sel:[0,1]
	v_cvt_pk_bf16_f32 v110, v114, v115
	v_lshl_add_u64 v[114:115], s[20:21], 0, v[118:119]
	v_lshlrev_b64 v[114:115], 9, v[114:115]
	v_cvt_pk_bf16_f32 v111, v116, v117
	v_lshl_add_u64 v[114:115], v[148:149], 0, v[114:115]
	v_cvt_pk_bf16_f32 v112, v112, v113
	v_cvt_pk_bf16_f32 v113, v120, v121
	global_store_dwordx4 v[114:115], v[110:113], off
	v_pk_mul_f32 v[108:109], v[108:109], v[134:135] op_sel:[0,1]
	v_pk_mul_f32 v[98:99], v[98:99], v[136:137] op_sel_hi:[1,0]
	v_pk_mul_f32 v[110:111], v[104:105], v[134:135] op_sel:[0,1]
	v_pk_mul_f32 v[104:105], v[102:103], v[134:135] op_sel:[0,1]
	v_cvt_pk_bf16_f32 v102, v106, v107
	v_cvt_pk_bf16_f32 v103, v108, v109
	v_pk_mul_f32 v[100:101], v[100:101], v[136:137] op_sel_hi:[1,0]
	v_cvt_pk_bf16_f32 v104, v104, v105
	v_cvt_pk_bf16_f32 v105, v110, v111
	global_store_dwordx4 v[114:115], v[102:105], off offset:256
	v_pk_mul_f32 v[88:89], v[88:89], v[136:137] op_sel_hi:[1,0]
	v_pk_mul_f32 v[86:87], v[86:87], v[136:137] op_sel_hi:[1,0]
	v_or_b32_e32 v102, 32, v154
	v_ashrrev_i32_e32 v103, 31, v102
	v_pk_mul_f32 v[104:105], v[92:93], v[136:137] op_sel_hi:[1,0]
	v_pk_mul_f32 v[92:93], v[90:91], v[136:137] op_sel_hi:[1,0]
	v_cvt_pk_bf16_f32 v90, v98, v99
	v_lshl_add_u64 v[98:99], s[20:21], 0, v[102:103]
	v_lshlrev_b64 v[98:99], 9, v[98:99]
	v_cvt_pk_bf16_f32 v91, v100, v101
	v_lshl_add_u64 v[98:99], v[148:149], 0, v[98:99]
	v_cvt_pk_bf16_f32 v92, v92, v93
	v_cvt_pk_bf16_f32 v93, v104, v105
	global_store_dwordx4 v[98:99], v[90:93], off
	v_pk_mul_f32 v[64:65], v[64:65], v[94:95] op_sel_hi:[1,0]
	v_pk_mul_f32 v[54:55], v[54:55], v[94:95] op_sel_hi:[1,0]
	v_pk_mul_f32 v[90:91], v[84:85], v[136:137] op_sel_hi:[1,0]
	v_pk_mul_f32 v[84:85], v[82:83], v[136:137] op_sel_hi:[1,0]
	v_cvt_pk_bf16_f32 v82, v86, v87
	v_cvt_pk_bf16_f32 v83, v88, v89
	v_pk_mul_f32 v[56:57], v[56:57], v[94:95] op_sel_hi:[1,0]
	v_cvt_pk_bf16_f32 v84, v84, v85
	v_cvt_pk_bf16_f32 v85, v90, v91
	global_store_dwordx4 v[98:99], v[82:85], off offset:256
	v_pk_mul_f32 v[50:51], v[50:51], v[94:95] op_sel:[0,1]
	v_pk_mul_f32 v[38:39], v[38:39], v[94:95] op_sel:[0,1]
	v_or_b32_e32 v84, 48, v154
	v_mov_b32_e32 v82, v137
	v_ashrrev_i32_e32 v85, 31, v84
	v_pk_mul_f32 v[78:79], v[78:79], v[82:83] op_sel_hi:[1,0]
	v_pk_mul_f32 v[74:75], v[74:75], v[82:83] op_sel_hi:[1,0]
	v_pk_mul_f32 v[80:81], v[80:81], v[82:83] op_sel_hi:[1,0]
	v_pk_mul_f32 v[86:87], v[76:77], v[82:83] op_sel_hi:[1,0]
	v_cvt_pk_bf16_f32 v76, v78, v79
	v_cvt_pk_bf16_f32 v77, v80, v81
	v_cvt_pk_bf16_f32 v78, v74, v75
	v_lshl_add_u64 v[74:75], s[20:21], 0, v[84:85]
	v_lshlrev_b64 v[74:75], 9, v[74:75]
	v_lshl_add_u64 v[74:75], v[148:149], 0, v[74:75]
; __device__ __forceinline__ unsigned cvt_pk_bf16(float lo, float hi) { unsigned r; asm volatile("v_cvt_pk_bf16_f32 %0, %1, %2" : "=v"(r) : "v"(lo), "v"(hi)); return r; }
;     __device__ __forceinline__ void operator()(const f32x4 (&acc)[2][2][4][2], const Unit& u, int wr, int wc, int fr, int fq) const {
;     ...
;             for (int m = 0; m < 4; ++m) { const int row = row0 + ai * HALF + m * 16; const float r = rs[ai][m];
; #pragma unroll
;                 for (int bj = 0; bj < 2; ++bj) { const f32x4 v0 = acc[ai][bj][m][0] * r, v1 = acc[ai][bj][m][1] * r;
;                     u32x4 w; w.x = cvt_pk_bf16(v0[0], v0[1]); w.y = cvt_pk_bf16(v0[2], v0[3]); w.z = cvt_pk_bf16(v1[0], v1[1]); w.w = cvt_pk_bf16(v1[2], v1[3]);
;                     *(u32x4*)(O + ((size_t)u.pn * Mrows + row) * 256 + bj * HALF + col0) = w; } }
;     }
	v_cvt_pk_bf16_f32 v79, v86, v87
	global_store_dwordx4 v[74:75], v[76:79], off
	v_pk_mul_f32 v[70:71], v[70:71], v[82:83] op_sel_hi:[1,0]
	v_pk_mul_f32 v[72:73], v[72:73], v[82:83] op_sel_hi:[1,0]
	v_pk_mul_f32 v[76:77], v[68:69], v[82:83] op_sel_hi:[1,0]
	v_pk_mul_f32 v[68:69], v[66:67], v[82:83] op_sel_hi:[1,0]
	v_cvt_pk_bf16_f32 v66, v70, v71
	v_cvt_pk_bf16_f32 v67, v72, v73
	v_pk_mul_f32 v[40:41], v[40:41], v[94:95] op_sel:[0,1]
	v_cvt_pk_bf16_f32 v68, v68, v69
	v_cvt_pk_bf16_f32 v69, v76, v77
	global_store_dwordx4 v[74:75], v[66:69], off offset:256
	v_pk_mul_f32 v[34:35], v[34:35], v[96:97] op_sel_hi:[1,0]
	v_pk_mul_f32 v[22:23], v[22:23], v[96:97] op_sel_hi:[1,0]
	v_add_u32_e32 v66, 0x80, v154
	v_ashrrev_i32_e32 v67, 31, v66
	v_pk_mul_f32 v[68:69], v[60:61], v[94:95] op_sel_hi:[1,0]
	v_pk_mul_f32 v[60:61], v[58:59], v[94:95] op_sel_hi:[1,0]
	v_cvt_pk_bf16_f32 v58, v62, v63
	v_lshl_add_u64 v[62:63], s[20:21], 0, v[66:67]
	v_lshlrev_b64 v[62:63], 9, v[62:63]
	v_cvt_pk_bf16_f32 v59, v64, v65
	v_lshl_add_u64 v[62:63], v[148:149], 0, v[62:63]
	v_cvt_pk_bf16_f32 v60, v60, v61
	v_cvt_pk_bf16_f32 v61, v68, v69
	global_store_dwordx4 v[62:63], v[58:61], off
	v_pk_mul_f32 v[24:25], v[24:25], v[96:97] op_sel_hi:[1,0]
	s_nop 0
	v_pk_mul_f32 v[58:59], v[48:49], v[94:95] op_sel_hi:[1,0]
	v_pk_mul_f32 v[48:49], v[46:47], v[94:95] op_sel_hi:[1,0]
	v_cvt_pk_bf16_f32 v46, v54, v55
	v_cvt_pk_bf16_f32 v47, v56, v57
	s_nop 0
	v_cvt_pk_bf16_f32 v48, v48, v49
	v_cvt_pk_bf16_f32 v49, v58, v59
	global_store_dwordx4 v[62:63], v[46:49], off offset:256
	s_nop 1
	v_add_u32_e32 v46, 0x90, v154
	v_ashrrev_i32_e32 v47, 31, v46
	v_lshl_add_u64 v[46:47], s[20:21], 0, v[46:47]
	v_lshlrev_b64 v[46:47], 9, v[46:47]
	v_pk_mul_f32 v[48:49], v[52:53], v[94:95] op_sel:[0,1]
	v_pk_mul_f32 v[52:53], v[44:45], v[94:95] op_sel:[0,1]
	v_pk_mul_f32 v[44:45], v[42:43], v[94:95] op_sel:[0,1]
	v_cvt_pk_bf16_f32 v42, v50, v51
	v_cvt_pk_bf16_f32 v43, v48, v49
	v_lshl_add_u64 v[46:47], v[148:149], 0, v[46:47]
	v_cvt_pk_bf16_f32 v44, v44, v45
	v_cvt_pk_bf16_f32 v45, v52, v53
	global_store_dwordx4 v[46:47], v[42:45], off
	s_nop 1
	v_pk_mul_f32 v[42:43], v[32:33], v[94:95] op_sel:[0,1]
	v_pk_mul_f32 v[32:33], v[30:31], v[94:95] op_sel:[0,1]
	v_cvt_pk_bf16_f32 v30, v38, v39
	v_cvt_pk_bf16_f32 v31, v40, v41
	s_nop 0
	v_cvt_pk_bf16_f32 v32, v32, v33
	v_cvt_pk_bf16_f32 v33, v42, v43
	global_store_dwordx4 v[46:47], v[30:33], off offset:256
	s_nop 1
	v_add_u32_e32 v30, 0xa0, v154
	v_ashrrev_i32_e32 v31, 31, v30
	v_lshl_add_u64 v[30:31], s[20:21], 0, v[30:31]
	v_lshlrev_b64 v[30:31], 9, v[30:31]
	v_pk_mul_f32 v[32:33], v[36:37], v[96:97] op_sel_hi:[1,0]
	v_pk_mul_f32 v[36:37], v[28:29], v[96:97] op_sel_hi:[1,0]
	v_pk_mul_f32 v[28:29], v[26:27], v[96:97] op_sel_hi:[1,0]
	v_cvt_pk_bf16_f32 v26, v34, v35
	v_cvt_pk_bf16_f32 v27, v32, v33
	v_lshl_add_u64 v[30:31], v[148:149], 0, v[30:31]
	v_cvt_pk_bf16_f32 v28, v28, v29
	v_cvt_pk_bf16_f32 v29, v36, v37
	global_store_dwordx4 v[30:31], v[26:29], off
	s_nop 1
	v_pk_mul_f32 v[26:27], v[16:17], v[96:97] op_sel_hi:[1,0]
	v_pk_mul_f32 v[16:17], v[14:15], v[96:97] op_sel_hi:[1,0]
	v_cvt_pk_bf16_f32 v14, v22, v23
	v_cvt_pk_bf16_f32 v15, v24, v25
	s_nop 0
	v_cvt_pk_bf16_f32 v16, v16, v17
	v_cvt_pk_bf16_f32 v17, v26, v27
	global_store_dwordx4 v[30:31], v[14:17], off offset:256
	s_nop 1
	v_add_u32_e32 v14, 0xb0, v154
	v_ashrrev_i32_e32 v15, 31, v14
	v_lshl_add_u64 v[14:15], s[20:21], 0, v[14:15]
	v_mov_b32_e32 v16, v97
	v_lshlrev_b64 v[14:15], 9, v[14:15]
	v_pk_mul_f32 v[20:21], v[20:21], v[16:17] op_sel_hi:[1,0]
	v_pk_mul_f32 v[18:19], v[18:19], v[16:17] op_sel_hi:[1,0]
	v_pk_mul_f32 v[22:23], v[12:13], v[16:17] op_sel_hi:[1,0]
	v_pk_mul_f32 v[12:13], v[10:11], v[16:17] op_sel_hi:[1,0]
	v_cvt_pk_bf16_f32 v10, v18, v19
	v_cvt_pk_bf16_f32 v11, v20, v21
	v_lshl_add_u64 v[14:15], v[148:149], 0, v[14:15]
	v_cvt_pk_bf16_f32 v12, v12, v13
	v_cvt_pk_bf16_f32 v13, v22, v23
	global_store_dwordx4 v[14:15], v[10:13], off
	s_mov_b64 s[20:21], -1
	v_pk_mul_f32 v[8:9], v[8:9], v[16:17] op_sel_hi:[1,0]
	v_pk_mul_f32 v[10:11], v[4:5], v[16:17] op_sel_hi:[1,0]
	v_pk_mul_f32 v[4:5], v[2:3], v[16:17] op_sel_hi:[1,0]
	v_pk_mul_f32 v[6:7], v[6:7], v[16:17] op_sel_hi:[1,0]
	s_nop 0
	v_cvt_pk_bf16_f32 v2, v6, v7
	v_cvt_pk_bf16_f32 v3, v8, v9
	v_cvt_pk_bf16_f32 v4, v4, v5
	v_cvt_pk_bf16_f32 v5, v10, v11
	global_store_dwordx4 v[14:15], v[2:5], off offset:256
	s_cbranch_vccnz .LBB0_297
	s_andn2_b64 vcc, exec, s[6:7]
	s_cbranch_vccnz .LBB0_296
	s_barrier
	s_branch .LBB0_296

;     __host__ __device__ bool next(int i, Unit& u) const {
;         const long L = (long)i * G + c; if (L >= nwg) return false;
;         int wgid = (int)L; { const int q = nwg / NXCD, r = nwg % NXCD, xcd = wgid % NXCD, off = wgid / NXCD; wgid = (xcd < r ? xcd * (q + 1) : r * (q + 1) + (xcd - r) * q) + off; }
;         const int nig = WGM * nN, gid = wgid / nig, fm = gid * WGM, gsz = (nM - fm) < WGM ? (nM - fm) : WGM;
;         u.pm = fm + ((wgid % nig) % gsz); u.pn = (wgid % nig) / gsz; return true;
;     __device__ __forceinline__ void operator()(const f32x4 (&acc)[2][2][4][2], const Unit& u, int wr, int wc, int fr, int fq) const {
;     ...
;         { const f32x4 r0 = *(const f32x4*)(rstd + u.pm * BM + (wr * 16 + fr) * 8), r1 = *(const f32x4*)(rstd + u.pm * BM + (wr * 16 + fr) * 8 + 4);
.LBB0_315:
	s_lshl_b32 s4, s22, 8
	s_ashr_i32 s5, s4, 31
	v_lshl_add_u64 v[242:243], s[4:5], 2, v[146:147]
	global_load_dwordx4 v[246:249], v[242:243], off offset:16
	s_nop 0
	global_load_dwordx4 v[242:245], v[242:243], off
	s_add_i32 s43, s43, 1
	s_mul_i32 s4, s43, s42
	s_mul_hi_u32 s5, s43, s30
	s_add_i32 s5, s5, s4
	s_mul_i32 s4, s43, s30
	s_add_u32 s16, s4, s31
	s_addc_u32 s17, s5, s36
	v_mov_b64_e32 v[2:3], 0x700
	v_cmp_lt_i64_e64 s[4:5], s[16:17], v[2:3]
	v_mov_b64_e32 v[2:3], 0x6ff
	v_cmp_gt_i64_e32 vcc, s[16:17], v[2:3]
	s_cbranch_vccnz .LBB0_317
	s_ashr_i32 s10, s16, 31
	s_lshr_b32 s10, s10, 29
	s_add_i32 s10, s16, s10
	s_ashr_i32 s11, s10, 3
	s_and_b32 s10, s10, -8
	s_sub_i32 s10, s16, s10
	s_cmp_lt_i32 s10, 0
	s_cselect_b32 s12, s51, 0xe0
	s_mul_i32 s10, s10, s12
	s_add_i32 s10, s10, s11
	s_mul_hi_i32 s11, s10, 0x92492493
	s_add_i32 s11, s11, s10
	s_lshr_b32 s12, s11, 31
	s_ashr_i32 s11, s11, 6
	s_add_i32 s11, s11, s12
	s_lshl_b32 s12, s11, 3
	s_sub_i32 s13, 0x80, s12
	s_min_i32 s13, s13, 8
	s_abs_i32 s16, s13
	v_cvt_f32_u32_e32 v2, s16
	s_sub_i32 s18, 0, s16
	s_mulk_i32 s11, 0x70
	s_sub_i32 s11, s10, s11
	v_rcp_iflag_f32_e32 v2, v2
	s_abs_i32 s10, s11
	s_xor_b32 s17, s11, s13
	s_ashr_i32 s17, s17, 31
	v_mul_f32_e32 v2, 0x4f7ffffe, v2
	v_cvt_u32_f32_e32 v2, v2
	s_nop 0
	v_readfirstlane_b32 s19, v2
	s_mul_i32 s18, s18, s19
	s_mul_hi_u32 s18, s19, s18
	s_add_i32 s19, s19, s18
	s_mul_hi_u32 s18, s10, s19
	s_mul_i32 s19, s18, s16
	s_sub_i32 s10, s10, s19
	s_add_i32 s21, s18, 1
	s_sub_i32 s19, s10, s16
	s_cmp_ge_u32 s10, s16
	s_cselect_b32 s18, s21, s18
	s_cselect_b32 s10, s19, s10
	s_add_i32 s19, s18, 1
	s_cmp_ge_u32 s10, s16
	s_cselect_b32 s10, s19, s18
	s_xor_b32 s10, s10, s17
	s_sub_i32 s10, s10, s17
	s_mul_i32 s13, s10, s13
	s_sub_i32 s11, s11, s13
	s_add_i32 s12, s12, s11

; __device__ __forceinline__ unsigned cvt_pk_bf16(float lo, float hi) { unsigned r; asm volatile("v_cvt_pk_bf16_f32 %0, %1, %2" : "=v"(r) : "v"(lo), "v"(hi)); return r; }
;     __device__ __forceinline__ void operator()(const f32x4 (&acc)[2][2][4][2], const Unit& u, int wr, int wc, int fr, int fq) const {
;         const int row0 = u.pm * BM + wr * 64 + fr; const int col0 = wc * 32 + 8 * fq;
;         float rs[2][4];
;         { const f32x4 r0 = *(const f32x4*)(rstd + u.pm * BM + (wr * 16 + fr) * 8), r1 = *(const f32x4*)(rstd + u.pm * BM + (wr * 16 + fr) * 8 + 4);
; #pragma unroll
;           for (int m = 0; m < 4; ++m) { rs[0][m] = r0[m]; rs[1][m] = r1[m]; } }
; #pragma unroll
;         for (int ai = 0; ai < 2; ++ai)
; #pragma unroll
;             for (int m = 0; m < 4; ++m) { const int row = row0 + ai * HALF + m * 16; const float r = rs[ai][m];
; #pragma unroll
;                 for (int bj = 0; bj < 2; ++bj) { const f32x4 v0 = acc[ai][bj][m][0] * r, v1 = acc[ai][bj][m][1] * r;
;                     u32x4 w; w.x = cvt_pk_bf16(v0[0], v0[1]); w.y = cvt_pk_bf16(v0[2], v0[3]); w.z = cvt_pk_bf16(v1[0], v1[1]); w.w = cvt_pk_bf16(v1[2], v1[3]);
;                     *(u32x4*)(O + ((size_t)u.pn * Mrows + row) * 256 + bj * HALF + col0) = w; } }
;     }
.LBB0_321:
	s_lshl_b32 s24, s22, 8
	s_ashr_i32 s25, s24, 31
	v_mov_b64_e32 v[94:95], v[246:247]
	v_mov_b64_e32 v[96:97], v[248:249]
	v_mov_b64_e32 v[134:135], v[242:243]
	v_mov_b64_e32 v[136:137], v[244:245]
	v_add_u32_e32 v154, s24, v1
	s_ashr_i32 s21, s20, 31
	v_ashrrev_i32_e32 v155, 31, v154
	s_lshl_b64 s[20:21], s[20:21], 15
	s_andn2_b64 vcc, exec, s[4:5]
	v_pk_mul_f32 v[62:63], v[62:63], v[94:95] op_sel_hi:[1,0]
	v_pk_mul_f32 v[130:131], v[130:131], v[134:135] op_sel_hi:[1,0]
	v_pk_mul_f32 v[158:159], v[128:129], v[134:135] op_sel_hi:[1,0]
	v_pk_mul_f32 v[128:129], v[126:127], v[134:135] op_sel_hi:[1,0]
	v_cvt_pk_bf16_f32 v126, v130, v131
	v_lshl_add_u64 v[130:131], s[20:21], 0, v[154:155]
	v_lshlrev_b64 v[130:131], 9, v[130:131]
	v_pk_mul_f32 v[132:133], v[132:133], v[134:135] op_sel_hi:[1,0]
	v_lshl_add_u64 v[130:131], v[148:149], 0, v[130:131]
	v_cvt_pk_bf16_f32 v127, v132, v133
	v_cvt_pk_bf16_f32 v128, v128, v129
	v_cvt_pk_bf16_f32 v129, v158, v159
	global_store_dwordx4 v[130:131], v[126:129], off
	v_pk_mul_f32 v[122:123], v[122:123], v[134:135] op_sel_hi:[1,0]
	v_pk_mul_f32 v[124:125], v[124:125], v[134:135] op_sel_hi:[1,0]
	v_pk_mul_f32 v[126:127], v[120:121], v[134:135] op_sel_hi:[1,0]
	v_pk_mul_f32 v[120:121], v[118:119], v[134:135] op_sel_hi:[1,0]
	v_cvt_pk_bf16_f32 v118, v122, v123
	v_cvt_pk_bf16_f32 v119, v124, v125
	v_pk_mul_f32 v[114:115], v[114:115], v[134:135] op_sel:[0,1]
	v_cvt_pk_bf16_f32 v120, v120, v121
	v_cvt_pk_bf16_f32 v121, v126, v127
	global_store_dwordx4 v[130:131], v[118:121], off offset:256
	v_pk_mul_f32 v[116:117], v[116:117], v[134:135] op_sel:[0,1]
	v_pk_mul_f32 v[106:107], v[106:107], v[134:135] op_sel:[0,1]
	v_or_b32_e32 v118, 16, v154
	v_ashrrev_i32_e32 v119, 31, v118
	v_pk_mul_f32 v[120:121], v[112:113], v[134:135] op_sel:[0,1]
	v_pk_mul_f32 v[112:113], v[110:111], v[134:135] op_sel:[0,1]
	v_cvt_pk_bf16_f32 v110, v114, v115
	v_lshl_add_u64 v[114:115], s[20:21], 0, v[118:119]
	v_lshlrev_b64 v[114:115], 9, v[114:115]
	v_cvt_pk_bf16_f32 v111, v116, v117
	v_lshl_add_u64 v[114:115], v[148:149], 0, v[114:115]
	v_cvt_pk_bf16_f32 v112, v112, v113
	v_cvt_pk_bf16_f32 v113, v120, v121
	global_store_dwordx4 v[114:115], v[110:113], off
	v_pk_mul_f32 v[108:109], v[108:109], v[134:135] op_sel:[0,1]
	v_pk_mul_f32 v[98:99], v[98:99], v[136:137] op_sel_hi:[1,0]
	v_pk_mul_f32 v[110:111], v[104:105], v[134:135] op_sel:[0,1]
	v_pk_mul_f32 v[104:105], v[102:103], v[134:135] op_sel:[0,1]
	v_cvt_pk_bf16_f32 v102, v106, v107
	v_cvt_pk_bf16_f32 v103, v108, v109
	v_pk_mul_f32 v[100:101], v[100:101], v[136:137] op_sel_hi:[1,0]
	v_cvt_pk_bf16_f32 v104, v104, v105
	v_cvt_pk_bf16_f32 v105, v110, v111
	global_store_dwordx4 v[114:115], v[102:105], off offset:256
	v_pk_mul_f32 v[88:89], v[88:89], v[136:137] op_sel_hi:[1,0]
	v_pk_mul_f32 v[86:87], v[86:87], v[136:137] op_sel_hi:[1,0]
	v_or_b32_e32 v102, 32, v154
	v_ashrrev_i32_e32 v103, 31, v102
	v_pk_mul_f32 v[104:105], v[92:93], v[136:137] op_sel_hi:[1,0]
	v_pk_mul_f32 v[92:93], v[90:91], v[136:137] op_sel_hi:[1,0]
	v_cvt_pk_bf16_f32 v90, v98, v99
	v_lshl_add_u64 v[98:99], s[20:21], 0, v[102:103]
	v_lshlrev_b64 v[98:99], 9, v[98:99]
	v_cvt_pk_bf16_f32 v91, v100, v101
	v_lshl_add_u64 v[98:99], v[148:149], 0, v[98:99]
	v_cvt_pk_bf16_f32 v92, v92, v93
	v_cvt_pk_bf16_f32 v93, v104, v105
	global_store_dwordx4 v[98:99], v[90:93], off
	v_pk_mul_f32 v[64:65], v[64:65], v[94:95] op_sel_hi:[1,0]
	v_pk_mul_f32 v[54:55], v[54:55], v[94:95] op_sel_hi:[1,0]
	v_pk_mul_f32 v[90:91], v[84:85], v[136:137] op_sel_hi:[1,0]
	v_pk_mul_f32 v[84:85], v[82:83], v[136:137] op_sel_hi:[1,0]
	v_cvt_pk_bf16_f32 v82, v86, v87
	v_cvt_pk_bf16_f32 v83, v88, v89
	v_pk_mul_f32 v[56:57], v[56:57], v[94:95] op_sel_hi:[1,0]
	v_cvt_pk_bf16_f32 v84, v84, v85
	v_cvt_pk_bf16_f32 v85, v90, v91
	global_store_dwordx4 v[98:99], v[82:85], off offset:256
	v_pk_mul_f32 v[50:51], v[50:51], v[94:95] op_sel:[0,1]
	v_pk_mul_f32 v[38:39], v[38:39], v[94:95] op_sel:[0,1]
	v_or_b32_e32 v84, 48, v154
	v_mov_b32_e32 v82, v137
	v_ashrrev_i32_e32 v85, 31, v84
	v_pk_mul_f32 v[78:79], v[78:79], v[82:83] op_sel_hi:[1,0]
	v_pk_mul_f32 v[74:75], v[74:75], v[82:83] op_sel_hi:[1,0]
	v_pk_mul_f32 v[80:81], v[80:81], v[82:83] op_sel_hi:[1,0]
	v_pk_mul_f32 v[86:87], v[76:77], v[82:83] op_sel_hi:[1,0]
	v_cvt_pk_bf16_f32 v76, v78, v79
	v_cvt_pk_bf16_f32 v77, v80, v81
	v_cvt_pk_bf16_f32 v78, v74, v75
	v_lshl_add_u64 v[74:75], s[20:21], 0, v[84:85]
	v_lshlrev_b64 v[74:75], 9, v[74:75]
	v_lshl_add_u64 v[74:75], v[148:149], 0, v[74:75]
; __device__ __forceinline__ unsigned cvt_pk_bf16(float lo, float hi) { unsigned r; asm volatile("v_cvt_pk_bf16_f32 %0, %1, %2" : "=v"(r) : "v"(lo), "v"(hi)); return r; }
;     __device__ __forceinline__ void operator()(const f32x4 (&acc)[2][2][4][2], const Unit& u, int wr, int wc, int fr, int fq) const {
;     ...
;             for (int m = 0; m < 4; ++m) { const int row = row0 + ai * HALF + m * 16; const float r = rs[ai][m];
; #pragma unroll
;                 for (int bj = 0; bj < 2; ++bj) { const f32x4 v0 = acc[ai][bj][m][0] * r, v1 = acc[ai][bj][m][1] * r;
;                     u32x4 w; w.x = cvt_pk_bf16(v0[0], v0[1]); w.y = cvt_pk_bf16(v0[2], v0[3]); w.z = cvt_pk_bf16(v1[0], v1[1]); w.w = cvt_pk_bf16(v1[2], v1[3]);
;                     *(u32x4*)(O + ((size_t)u.pn * Mrows + row) * 256 + bj * HALF + col0) = w; } }
;     }
	v_cvt_pk_bf16_f32 v79, v86, v87
	global_store_dwordx4 v[74:75], v[76:79], off
	v_pk_mul_f32 v[70:71], v[70:71], v[82:83] op_sel_hi:[1,0]
	v_pk_mul_f32 v[72:73], v[72:73], v[82:83] op_sel_hi:[1,0]
	v_pk_mul_f32 v[76:77], v[68:69], v[82:83] op_sel_hi:[1,0]
	v_pk_mul_f32 v[68:69], v[66:67], v[82:83] op_sel_hi:[1,0]
	v_cvt_pk_bf16_f32 v66, v70, v71
	v_cvt_pk_bf16_f32 v67, v72, v73
	v_pk_mul_f32 v[40:41], v[40:41], v[94:95] op_sel:[0,1]
	v_cvt_pk_bf16_f32 v68, v68, v69
	v_cvt_pk_bf16_f32 v69, v76, v77
	global_store_dwordx4 v[74:75], v[66:69], off offset:256
	v_pk_mul_f32 v[34:35], v[34:35], v[96:97] op_sel_hi:[1,0]
	v_pk_mul_f32 v[22:23], v[22:23], v[96:97] op_sel_hi:[1,0]
	v_add_u32_e32 v66, 0x80, v154
	v_ashrrev_i32_e32 v67, 31, v66
	v_pk_mul_f32 v[68:69], v[60:61], v[94:95] op_sel_hi:[1,0]
	v_pk_mul_f32 v[60:61], v[58:59], v[94:95] op_sel_hi:[1,0]
	v_cvt_pk_bf16_f32 v58, v62, v63
	v_lshl_add_u64 v[62:63], s[20:21], 0, v[66:67]
	v_lshlrev_b64 v[62:63], 9, v[62:63]
	v_cvt_pk_bf16_f32 v59, v64, v65
	v_lshl_add_u64 v[62:63], v[148:149], 0, v[62:63]
	v_cvt_pk_bf16_f32 v60, v60, v61
	v_cvt_pk_bf16_f32 v61, v68, v69
	global_store_dwordx4 v[62:63], v[58:61], off
	v_pk_mul_f32 v[24:25], v[24:25], v[96:97] op_sel_hi:[1,0]
	s_nop 0
	v_pk_mul_f32 v[58:59], v[48:49], v[94:95] op_sel_hi:[1,0]
	v_pk_mul_f32 v[48:49], v[46:47], v[94:95] op_sel_hi:[1,0]
	v_cvt_pk_bf16_f32 v46, v54, v55
	v_cvt_pk_bf16_f32 v47, v56, v57
	s_nop 0
	v_cvt_pk_bf16_f32 v48, v48, v49
	v_cvt_pk_bf16_f32 v49, v58, v59
	global_store_dwordx4 v[62:63], v[46:49], off offset:256
	s_nop 1
	v_add_u32_e32 v46, 0x90, v154
	v_ashrrev_i32_e32 v47, 31, v46
	v_lshl_add_u64 v[46:47], s[20:21], 0, v[46:47]
	v_lshlrev_b64 v[46:47], 9, v[46:47]
	v_pk_mul_f32 v[48:49], v[52:53], v[94:95] op_sel:[0,1]
	v_pk_mul_f32 v[52:53], v[44:45], v[94:95] op_sel:[0,1]
	v_pk_mul_f32 v[44:45], v[42:43], v[94:95] op_sel:[0,1]
	v_cvt_pk_bf16_f32 v42, v50, v51
	v_cvt_pk_bf16_f32 v43, v48, v49
	v_lshl_add_u64 v[46:47], v[148:149], 0, v[46:47]
	v_cvt_pk_bf16_f32 v44, v44, v45
	v_cvt_pk_bf16_f32 v45, v52, v53
	global_store_dwordx4 v[46:47], v[42:45], off
	s_nop 1
	v_pk_mul_f32 v[42:43], v[32:33], v[94:95] op_sel:[0,1]
	v_pk_mul_f32 v[32:33], v[30:31], v[94:95] op_sel:[0,1]
	v_cvt_pk_bf16_f32 v30, v38, v39
	v_cvt_pk_bf16_f32 v31, v40, v41
	s_nop 0
	v_cvt_pk_bf16_f32 v32, v32, v33
	v_cvt_pk_bf16_f32 v33, v42, v43
	global_store_dwordx4 v[46:47], v[30:33], off offset:256
	s_nop 1
	v_add_u32_e32 v30, 0xa0, v154
	v_ashrrev_i32_e32 v31, 31, v30
	v_lshl_add_u64 v[30:31], s[20:21], 0, v[30:31]
	v_lshlrev_b64 v[30:31], 9, v[30:31]
	v_pk_mul_f32 v[32:33], v[36:37], v[96:97] op_sel_hi:[1,0]
	v_pk_mul_f32 v[36:37], v[28:29], v[96:97] op_sel_hi:[1,0]
	v_pk_mul_f32 v[28:29], v[26:27], v[96:97] op_sel_hi:[1,0]
	v_cvt_pk_bf16_f32 v26, v34, v35
	v_cvt_pk_bf16_f32 v27, v32, v33
	v_lshl_add_u64 v[30:31], v[148:149], 0, v[30:31]
	v_cvt_pk_bf16_f32 v28, v28, v29
	v_cvt_pk_bf16_f32 v29, v36, v37
	global_store_dwordx4 v[30:31], v[26:29], off
	s_nop 1
	v_pk_mul_f32 v[26:27], v[16:17], v[96:97] op_sel_hi:[1,0]
	v_pk_mul_f32 v[16:17], v[14:15], v[96:97] op_sel_hi:[1,0]
	v_cvt_pk_bf16_f32 v14, v22, v23
	v_cvt_pk_bf16_f32 v15, v24, v25
	s_nop 0
	v_cvt_pk_bf16_f32 v16, v16, v17
	v_cvt_pk_bf16_f32 v17, v26, v27
	global_store_dwordx4 v[30:31], v[14:17], off offset:256
	s_nop 1
	v_add_u32_e32 v14, 0xb0, v154
	v_ashrrev_i32_e32 v15, 31, v14
	v_lshl_add_u64 v[14:15], s[20:21], 0, v[14:15]
	v_mov_b32_e32 v16, v97
	v_lshlrev_b64 v[14:15], 9, v[14:15]
	v_pk_mul_f32 v[20:21], v[20:21], v[16:17] op_sel_hi:[1,0]
	v_pk_mul_f32 v[18:19], v[18:19], v[16:17] op_sel_hi:[1,0]
	v_pk_mul_f32 v[22:23], v[12:13], v[16:17] op_sel_hi:[1,0]
	v_pk_mul_f32 v[12:13], v[10:11], v[16:17] op_sel_hi:[1,0]
	v_cvt_pk_bf16_f32 v10, v18, v19
	v_cvt_pk_bf16_f32 v11, v20, v21
	v_lshl_add_u64 v[14:15], v[148:149], 0, v[14:15]
	v_cvt_pk_bf16_f32 v12, v12, v13
	v_cvt_pk_bf16_f32 v13, v22, v23
	global_store_dwordx4 v[14:15], v[10:13], off
	s_mov_b64 s[20:21], -1
	v_pk_mul_f32 v[8:9], v[8:9], v[16:17] op_sel_hi:[1,0]
	v_pk_mul_f32 v[10:11], v[4:5], v[16:17] op_sel_hi:[1,0]
	v_pk_mul_f32 v[4:5], v[2:3], v[16:17] op_sel_hi:[1,0]
	v_pk_mul_f32 v[6:7], v[6:7], v[16:17] op_sel_hi:[1,0]
	s_nop 0
	v_cvt_pk_bf16_f32 v2, v6, v7
	v_cvt_pk_bf16_f32 v3, v8, v9
	v_cvt_pk_bf16_f32 v4, v4, v5
	v_cvt_pk_bf16_f32 v5, v10, v11
	global_store_dwordx4 v[14:15], v[2:5], off offset:256
	s_cbranch_vccnz .LBB0_314
	s_andn2_b64 vcc, exec, s[0:1]
	s_cbranch_vccnz .LBB0_313
	s_barrier
	s_branch .LBB0_313

;     __host__ __device__ bool next(int i, Unit& u) const {
;         const long L = (long)i * G + c; if (L >= nwg) return false;
;         int wgid = (int)L; { const int q = nwg / NXCD, r = nwg % NXCD, xcd = wgid % NXCD, off = wgid / NXCD; wgid = (xcd < r ? xcd * (q + 1) : r * (q + 1) + (xcd - r) * q) + off; }
;         const int nig = WGM * nN, gid = wgid / nig, fm = gid * WGM, gsz = (nM - fm) < WGM ? (nM - fm) : WGM;
;         u.pm = fm + ((wgid % nig) % gsz); u.pn = (wgid % nig) / gsz; return true;
;     __device__ __forceinline__ void operator()(const f32x4 (&acc)[2][2][4][2], const Unit& u, int wr, int wc, int fr, int fq) const {
;     ...
;         { const f32x4 r0 = *(const f32x4*)(rstd + u.pm * BM + (wr * 16 + fr) * 8), r1 = *(const f32x4*)(rstd + u.pm * BM + (wr * 16 + fr) * 8 + 4);
.LBB0_1246:
	s_lshl_b32 s4, s22, 8
	s_ashr_i32 s5, s4, 31
	v_lshl_add_u64 v[242:243], s[4:5], 2, v[146:147]
	global_load_dwordx4 v[246:249], v[242:243], off offset:16
	s_nop 0
	global_load_dwordx4 v[242:245], v[242:243], off
	s_add_i32 s44, s44, 1
	s_mul_i32 s4, s44, s43
	s_mul_hi_u32 s5, s44, s30
	s_add_i32 s5, s5, s4
	s_mul_i32 s4, s44, s30
	s_add_u32 s18, s4, s31
	s_addc_u32 s19, s5, s37
	v_mov_b64_e32 v[2:3], 0xb00
	v_cmp_lt_i64_e64 s[4:5], s[18:19], v[2:3]
	v_mov_b64_e32 v[2:3], 0xaff
	v_cmp_gt_i64_e32 vcc, s[18:19], v[2:3]
	s_cbranch_vccnz .LBB0_1248
	s_ashr_i32 s14, s18, 31
	s_lshr_b32 s14, s14, 29
	s_add_i32 s14, s18, s14
	s_ashr_i32 s15, s14, 3
	s_and_b32 s14, s14, -8
	s_sub_i32 s14, s18, s14
	s_cmp_lt_i32 s14, 0
	s_cselect_b32 s16, s55, 0x160
	s_mul_i32 s14, s14, s16
	s_add_i32 s14, s14, s15
	s_mul_hi_i32 s15, s14, 0x2e8ba2e9
	s_lshr_b32 s16, s15, 31
	s_ashr_i32 s15, s15, 5
	s_add_i32 s15, s15, s16
	s_lshl_b32 s16, s15, 3
	s_sub_i32 s17, 0x80, s16
	s_min_i32 s17, s17, 8
	s_abs_i32 s18, s17
	v_cvt_f32_u32_e32 v2, s18
	s_sub_i32 s20, 0, s18
	s_mulk_i32 s15, 0xb0
	s_sub_i32 s15, s14, s15
	v_rcp_iflag_f32_e32 v2, v2
	s_abs_i32 s14, s15
	s_xor_b32 s19, s15, s17
	s_ashr_i32 s19, s19, 31
	v_mul_f32_e32 v2, 0x4f7ffffe, v2
	v_cvt_u32_f32_e32 v2, v2
	s_nop 0
	v_readfirstlane_b32 s21, v2
	s_mul_i32 s20, s20, s21
	s_mul_hi_u32 s20, s21, s20
	s_add_i32 s21, s21, s20
	s_mul_hi_u32 s20, s14, s21
	s_mul_i32 s21, s20, s18
	s_sub_i32 s14, s14, s21
	s_add_i32 s28, s20, 1
	s_sub_i32 s21, s14, s18
	s_cmp_ge_u32 s14, s18
	s_cselect_b32 s20, s28, s20
	s_cselect_b32 s14, s21, s14
	s_add_i32 s21, s20, 1
	s_cmp_ge_u32 s14, s18
	s_cselect_b32 s14, s21, s20
	s_xor_b32 s14, s14, s19
	s_sub_i32 s14, s14, s19
	s_mul_i32 s17, s14, s17
	s_sub_i32 s15, s15, s17
	s_add_i32 s16, s16, s15

; __device__ __forceinline__ unsigned cvt_pk_bf16(float lo, float hi) { unsigned r; asm volatile("v_cvt_pk_bf16_f32 %0, %1, %2" : "=v"(r) : "v"(lo), "v"(hi)); return r; }
; __device__ __forceinline__ float silu_f(float x) { return x * __builtin_amdgcn_rcpf(1.0f + __builtin_amdgcn_exp2f(-1.4426950408889634f * x)); }
;     __device__ __forceinline__ void operator()(const f32x4 (&acc)[2][2][4][2], const Unit& u, int wr, int wc, int fr, int fq) const {
;     ...
;         { const f32x4 r0 = *(const f32x4*)(rstd + u.pm * BM + (wr * 16 + fr) * 8), r1 = *(const f32x4*)(rstd + u.pm * BM + (wr * 16 + fr) * 8 + 4);
; #pragma unroll
;           for (int m = 0; m < 4; ++m) { rs[0][m] = r0[m]; rs[1][m] = r1[m]; } }
; #pragma unroll
;         for (int ai = 0; ai < 2; ++ai)
; #pragma unroll
;             for (int m = 0; m < 4; ++m) { bf16_t* rowp = O + (size_t)(row0 + ai * HALF + m * 16) * ldc + col0; const float r = rs[ai][m];
;                 const f32x4 g0 = acc[ai][0][m][0] * r, g1 = acc[ai][0][m][1] * r, u0 = acc[ai][1][m][0] * r, u1 = acc[ai][1][m][1] * r;
;                 f32x4 v0, v1;
; #pragma unroll
;                 for (int i = 0; i < 4; ++i) { v0[i] = silu_f(g0[i]) * u0[i]; v1[i] = silu_f(g1[i]) * u1[i]; }
;                 u32x4 w; w.x = cvt_pk_bf16(v0[0], v0[1]); w.y = cvt_pk_bf16(v0[2], v0[3]); w.z = cvt_pk_bf16(v1[0], v1[1]); w.w = cvt_pk_bf16(v1[2], v1[3]);
;                 *(u32x4*)rowp = w; }
.LBB0_1252:
	s_lshl_b32 s24, s22, 8
	s_ashr_i32 s25, s24, 31
	v_mov_b64_e32 v[66:67], v[246:247]
	v_mov_b64_e32 v[68:69], v[248:249]
	v_mov_b64_e32 v[118:119], v[242:243]
	v_mov_b64_e32 v[120:121], v[244:245]
	v_mov_b32_e32 v162, v130
	v_mov_b32_e32 v163, v134
	v_mov_b32_e32 v134, v131
	v_lshl_or_b32 v154, s23, 7, v159
	v_add_u32_e32 v161, s24, v1
	v_ashrrev_i32_e32 v155, 31, v154
	v_mov_b64_e32 v[152:153], s[10:11]
	s_movk_i32 s15, 0x1600
	v_mad_i64_i32 v[156:157], s[22:23], v161, s15, v[152:153]
	s_andn2_b64 vcc, exec, s[4:5]
	v_pk_mul_f32 v[162:163], v[162:163], v[118:119] op_sel_hi:[1,0]
	s_nop 0
	v_mul_f32_e32 v130, 0xbfb8aa3b, v163
	v_exp_f32_e32 v130, v130
	s_nop 0
	v_add_f32_e32 v130, 1.0, v130
	v_rcp_f32_e32 v130, v130
	s_nop 0
	v_mul_f32_e32 v130, v163, v130
	v_mul_f32_e32 v164, v162, v130
	v_mov_b32_e32 v162, v122
	v_mov_b32_e32 v163, v126
	v_pk_mul_f32 v[162:163], v[162:163], v[118:119] op_sel_hi:[1,0]
	v_pk_mul_f32 v[130:131], v[134:135], v[118:119] op_sel_hi:[1,0]
	v_mul_f32_e32 v122, 0xbfb8aa3b, v163
	v_exp_f32_e32 v122, v122
	v_mov_b32_e32 v126, v123
	v_add_f32_e32 v122, 1.0, v122
	v_rcp_f32_e32 v122, v122
	s_nop 0
	v_mul_f32_e32 v122, v163, v122
	v_mul_f32_e32 v162, v162, v122
	v_mul_f32_e32 v122, 0xbfb8aa3b, v131
	v_exp_f32_e32 v122, v122
	s_nop 0
	v_add_f32_e32 v122, 1.0, v122
	v_rcp_f32_e32 v122, v122
	s_nop 0
	v_mul_f32_e32 v122, v131, v122
	v_mul_f32_e32 v130, v130, v122
	v_pk_mul_f32 v[122:123], v[126:127], v[118:119] op_sel_hi:[1,0]
	s_nop 0
	v_mul_f32_e32 v126, 0xbfb8aa3b, v123
	v_exp_f32_e32 v126, v126
	s_nop 0
	v_add_f32_e32 v126, 1.0, v126
	v_rcp_f32_e32 v126, v126
	s_nop 0
	v_mul_f32_e32 v123, v123, v126
	v_mul_f32_e32 v126, v122, v123
	v_mov_b32_e32 v122, v132
	v_mov_b32_e32 v123, v136
	v_pk_mul_f32 v[122:123], v[122:123], v[118:119] op_sel_hi:[1,0]
	v_mov_b32_e32 v136, v133
	v_mul_f32_e32 v127, 0xbfb8aa3b, v123
	v_exp_f32_e32 v127, v127
	s_nop 0
	v_add_f32_e32 v127, 1.0, v127
	v_rcp_f32_e32 v127, v127
	s_nop 0
	v_mul_f32_e32 v123, v123, v127
	v_mul_f32_e32 v127, v122, v123
	v_mov_b32_e32 v122, v124
	v_mov_b32_e32 v123, v128
	v_pk_mul_f32 v[122:123], v[122:123], v[118:119] op_sel_hi:[1,0]
	v_mov_b32_e32 v128, v125
	v_mul_f32_e32 v124, 0xbfb8aa3b, v123
	v_exp_f32_e32 v124, v124
	s_nop 0
	v_add_f32_e32 v124, 1.0, v124
	v_rcp_f32_e32 v124, v124
	s_nop 0
	v_mul_f32_e32 v123, v123, v124
	v_mul_f32_e32 v131, v122, v123
	v_pk_mul_f32 v[122:123], v[136:137], v[118:119] op_sel_hi:[1,0]
	s_nop 0
	v_mul_f32_e32 v124, 0xbfb8aa3b, v123
	v_exp_f32_e32 v124, v124
	s_nop 0
	v_add_f32_e32 v124, 1.0, v124
	v_rcp_f32_e32 v124, v124
	s_nop 0
	v_mul_f32_e32 v123, v123, v124
	v_mul_f32_e32 v132, v122, v123
	v_pk_mul_f32 v[122:123], v[128:129], v[118:119] op_sel_hi:[1,0]
	s_nop 0
	v_mul_f32_e32 v124, 0xbfb8aa3b, v123
	v_exp_f32_e32 v124, v124
	s_nop 0
	v_add_f32_e32 v124, 1.0, v124
	v_rcp_f32_e32 v124, v124
	s_nop 0
	v_mul_f32_e32 v123, v123, v124
	v_mul_f32_e32 v133, v122, v123
	v_lshlrev_b64 v[122:123], 1, v[154:155]
	v_lshl_add_u64 v[128:129], v[156:157], 0, v[122:123]
	v_cvt_pk_bf16_f32 v124, v164, v130
	v_cvt_pk_bf16_f32 v125, v127, v132
	v_cvt_pk_bf16_f32 v126, v162, v126
	v_cvt_pk_bf16_f32 v127, v131, v133
	global_store_dwordx4 v[128:129], v[124:127], off
	s_nop 1
	v_mov_b32_e32 v126, v106
	v_mov_b32_e32 v127, v114
	v_pk_mul_f32 v[126:127], v[126:127], v[118:119] op_sel:[0,1]
	v_mov_b32_e32 v114, v107
	v_mul_f32_e32 v106, 0xbfb8aa3b, v127
	v_exp_f32_e32 v106, v106
	v_pk_mul_f32 v[114:115], v[114:115], v[118:119] op_sel:[0,1]
	v_or_b32_e32 v124, 16, v161
	v_mad_i64_i32 v[124:125], s[22:23], v124, s15, v[152:153]
	v_add_f32_e32 v106, 1.0, v106
	v_rcp_f32_e32 v106, v106
	s_nop 0
	v_mul_f32_e32 v106, v127, v106
	v_mul_f32_e32 v106, v126, v106
	v_mov_b32_e32 v126, v102
	v_mov_b32_e32 v127, v110
	v_pk_mul_f32 v[126:127], v[126:127], v[118:119] op_sel:[0,1]
	v_mov_b32_e32 v110, v103
	v_mul_f32_e32 v102, 0xbfb8aa3b, v127
	v_exp_f32_e32 v102, v102
	s_nop 0
	v_add_f32_e32 v102, 1.0, v102
	v_rcp_f32_e32 v102, v102
	s_nop 0
	v_mul_f32_e32 v102, v127, v102
	v_mul_f32_e32 v126, v126, v102
	v_mul_f32_e32 v102, 0xbfb8aa3b, v115
	v_exp_f32_e32 v102, v102
	s_nop 0
	v_add_f32_e32 v102, 1.0, v102
	v_rcp_f32_e32 v102, v102
	s_nop 0
	v_mul_f32_e32 v102, v115, v102
	v_mul_f32_e32 v107, v114, v102
	v_pk_mul_f32 v[102:103], v[110:111], v[118:119] op_sel:[0,1]
	s_nop 0
	v_mul_f32_e32 v110, 0xbfb8aa3b, v103
	v_exp_f32_e32 v110, v110
	s_nop 0
	v_add_f32_e32 v110, 1.0, v110
	v_rcp_f32_e32 v110, v110
	s_nop 0
	v_mul_f32_e32 v103, v103, v110
	v_mul_f32_e32 v110, v102, v103
	v_mov_b32_e32 v102, v108
	v_mov_b32_e32 v103, v116
	v_pk_mul_f32 v[102:103], v[102:103], v[118:119] op_sel:[0,1]
	v_mov_b32_e32 v116, v109
	v_mul_f32_e32 v108, 0xbfb8aa3b, v103
	v_exp_f32_e32 v108, v108
	s_nop 0
	v_add_f32_e32 v108, 1.0, v108
	v_rcp_f32_e32 v108, v108
	s_nop 0
	v_mul_f32_e32 v103, v103, v108
	v_mul_f32_e32 v111, v102, v103
	v_mov_b32_e32 v102, v104
	v_mov_b32_e32 v103, v112
	v_pk_mul_f32 v[102:103], v[102:103], v[118:119] op_sel:[0,1]
	v_mov_b32_e32 v112, v105
	v_mul_f32_e32 v104, 0xbfb8aa3b, v103
	v_exp_f32_e32 v104, v104
	v_lshl_add_u64 v[108:109], v[124:125], 0, v[122:123]
	v_add_f32_e32 v104, 1.0, v104
	v_rcp_f32_e32 v104, v104
	s_nop 0
	v_mul_f32_e32 v103, v103, v104
	v_mul_f32_e32 v114, v102, v103
	v_pk_mul_f32 v[102:103], v[116:117], v[118:119] op_sel:[0,1]
	s_nop 0
	v_mul_f32_e32 v104, 0xbfb8aa3b, v103
	v_exp_f32_e32 v104, v104
	s_nop 0
	v_add_f32_e32 v104, 1.0, v104
	v_rcp_f32_e32 v104, v104
	s_nop 0
	v_mul_f32_e32 v103, v103, v104
	v_mul_f32_e32 v104, v102, v103
	v_pk_mul_f32 v[102:103], v[112:113], v[118:119] op_sel:[0,1]
	s_nop 0
	v_mul_f32_e32 v105, 0xbfb8aa3b, v103
; __device__ __forceinline__ unsigned cvt_pk_bf16(float lo, float hi) { unsigned r; asm volatile("v_cvt_pk_bf16_f32 %0, %1, %2" : "=v"(r) : "v"(lo), "v"(hi)); return r; }
; __device__ __forceinline__ float silu_f(float x) { return x * __builtin_amdgcn_rcpf(1.0f + __builtin_amdgcn_exp2f(-1.4426950408889634f * x)); }
;     __device__ __forceinline__ void operator()(const f32x4 (&acc)[2][2][4][2], const Unit& u, int wr, int wc, int fr, int fq) const {
;     ...
;             for (int m = 0; m < 4; ++m) { bf16_t* rowp = O + (size_t)(row0 + ai * HALF + m * 16) * ldc + col0; const float r = rs[ai][m];
;                 const f32x4 g0 = acc[ai][0][m][0] * r, g1 = acc[ai][0][m][1] * r, u0 = acc[ai][1][m][0] * r, u1 = acc[ai][1][m][1] * r;
;                 f32x4 v0, v1;
; #pragma unroll
;                 for (int i = 0; i < 4; ++i) { v0[i] = silu_f(g0[i]) * u0[i]; v1[i] = silu_f(g1[i]) * u1[i]; }
;                 u32x4 w; w.x = cvt_pk_bf16(v0[0], v0[1]); w.y = cvt_pk_bf16(v0[2], v0[3]); w.z = cvt_pk_bf16(v1[0], v1[1]); w.w = cvt_pk_bf16(v1[2], v1[3]);
;                 *(u32x4*)rowp = w; }
	v_exp_f32_e32 v105, v105
	s_nop 0
	v_add_f32_e32 v105, 1.0, v105
	v_rcp_f32_e32 v105, v105
	s_nop 0
	v_mul_f32_e32 v103, v103, v105
	v_mul_f32_e32 v105, v102, v103
	v_cvt_pk_bf16_f32 v102, v106, v107
	v_cvt_pk_bf16_f32 v103, v111, v104
	v_cvt_pk_bf16_f32 v104, v126, v110
	v_cvt_pk_bf16_f32 v105, v114, v105
	global_store_dwordx4 v[108:109], v[102:105], off
	s_nop 1
	v_mov_b32_e32 v104, v90
	v_mov_b32_e32 v105, v98
	v_pk_mul_f32 v[104:105], v[104:105], v[120:121] op_sel_hi:[1,0]
	v_mov_b32_e32 v98, v91
	v_mul_f32_e32 v90, 0xbfb8aa3b, v105
	v_exp_f32_e32 v90, v90
	v_or_b32_e32 v102, 32, v161
	v_mad_i64_i32 v[102:103], s[22:23], v102, s15, v[152:153]
	v_add_f32_e32 v90, 1.0, v90
	v_rcp_f32_e32 v90, v90
	s_nop 0
	v_mul_f32_e32 v90, v105, v90
	v_mul_f32_e32 v106, v104, v90
	v_mov_b32_e32 v104, v86
	v_mov_b32_e32 v105, v94
	v_pk_mul_f32 v[104:105], v[104:105], v[120:121] op_sel_hi:[1,0]
	v_pk_mul_f32 v[90:91], v[98:99], v[120:121] op_sel_hi:[1,0]
	v_mul_f32_e32 v86, 0xbfb8aa3b, v105
	v_exp_f32_e32 v86, v86
	v_mov_b32_e32 v94, v87
	v_add_f32_e32 v86, 1.0, v86
	v_rcp_f32_e32 v86, v86
	s_nop 0
	v_mul_f32_e32 v86, v105, v86
	v_mul_f32_e32 v104, v104, v86
	v_mul_f32_e32 v86, 0xbfb8aa3b, v91
	v_exp_f32_e32 v86, v86
	s_nop 0
	v_add_f32_e32 v86, 1.0, v86
	v_rcp_f32_e32 v86, v86
	s_nop 0
	v_mul_f32_e32 v86, v91, v86
	v_mul_f32_e32 v98, v90, v86
	v_pk_mul_f32 v[86:87], v[94:95], v[120:121] op_sel_hi:[1,0]
	s_nop 0
	v_mul_f32_e32 v90, 0xbfb8aa3b, v87
	v_exp_f32_e32 v90, v90
	s_nop 0
	v_add_f32_e32 v90, 1.0, v90
	v_rcp_f32_e32 v90, v90
	s_nop 0
	v_mul_f32_e32 v87, v87, v90
	v_mul_f32_e32 v94, v86, v87
	v_mov_b32_e32 v86, v92
	v_mov_b32_e32 v87, v100
	v_pk_mul_f32 v[86:87], v[86:87], v[120:121] op_sel_hi:[1,0]
	v_mov_b32_e32 v100, v93
	v_mul_f32_e32 v90, 0xbfb8aa3b, v87
	v_exp_f32_e32 v90, v90
	s_nop 0
	v_add_f32_e32 v90, 1.0, v90
	v_rcp_f32_e32 v90, v90
	s_nop 0
	v_mul_f32_e32 v87, v87, v90
	v_mul_f32_e32 v92, v86, v87
	v_mov_b32_e32 v86, v88
	v_mov_b32_e32 v87, v96
	v_pk_mul_f32 v[86:87], v[86:87], v[120:121] op_sel_hi:[1,0]
	v_mov_b32_e32 v96, v89
	v_mul_f32_e32 v88, 0xbfb8aa3b, v87
	v_exp_f32_e32 v88, v88
	v_lshl_add_u64 v[90:91], v[102:103], 0, v[122:123]
	v_add_f32_e32 v88, 1.0, v88
	v_rcp_f32_e32 v88, v88
	s_nop 0
	v_mul_f32_e32 v87, v87, v88
	v_mul_f32_e32 v95, v86, v87
	v_pk_mul_f32 v[86:87], v[100:101], v[120:121] op_sel_hi:[1,0]
	s_nop 0
	v_mul_f32_e32 v88, 0xbfb8aa3b, v87
	v_exp_f32_e32 v88, v88
	s_nop 0
	v_add_f32_e32 v88, 1.0, v88
	v_rcp_f32_e32 v88, v88
	s_nop 0
	v_mul_f32_e32 v87, v87, v88
	v_mul_f32_e32 v88, v86, v87
	v_pk_mul_f32 v[86:87], v[96:97], v[120:121] op_sel_hi:[1,0]
	s_nop 0
	v_mul_f32_e32 v89, 0xbfb8aa3b, v87
	v_exp_f32_e32 v89, v89
	s_nop 0
	v_add_f32_e32 v89, 1.0, v89
	v_rcp_f32_e32 v89, v89
	s_nop 0
	v_mul_f32_e32 v87, v87, v89
	v_mul_f32_e32 v89, v86, v87
	v_cvt_pk_bf16_f32 v86, v106, v98
	v_cvt_pk_bf16_f32 v87, v92, v88
	v_cvt_pk_bf16_f32 v88, v104, v94
	v_cvt_pk_bf16_f32 v89, v95, v89
	global_store_dwordx4 v[90:91], v[86:89], off
	s_nop 1
	v_mov_b32_e32 v88, v74
	v_mov_b32_e32 v89, v82
	v_mov_b32_e32 v74, v121
	v_pk_mul_f32 v[88:89], v[88:89], v[74:75] op_sel_hi:[1,0]
	v_or_b32_e32 v86, 48, v161
	v_mul_f32_e32 v82, 0xbfb8aa3b, v89
	v_exp_f32_e32 v82, v82
	v_mad_i64_i32 v[86:87], s[22:23], v86, s15, v[152:153]
	v_add_f32_e32 v82, 1.0, v82
	v_rcp_f32_e32 v82, v82
	s_nop 0
	v_mul_f32_e32 v82, v89, v82
	v_mul_f32_e32 v90, v88, v82
	v_mov_b32_e32 v88, v70
	v_mov_b32_e32 v89, v78
	v_pk_mul_f32 v[88:89], v[88:89], v[74:75] op_sel_hi:[1,0]
	v_mov_b32_e32 v82, v75
	v_mul_f32_e32 v70, 0xbfb8aa3b, v89
	v_exp_f32_e32 v70, v70
	v_pk_mul_f32 v[82:83], v[82:83], v[74:75] op_sel_hi:[1,0]
	v_mov_b32_e32 v78, v71
	v_add_f32_e32 v70, 1.0, v70
	v_rcp_f32_e32 v70, v70
	s_nop 0
	v_mul_f32_e32 v70, v89, v70
	v_mul_f32_e32 v88, v88, v70
	v_mul_f32_e32 v70, 0xbfb8aa3b, v83
	v_exp_f32_e32 v70, v70
	s_nop 0
	v_add_f32_e32 v70, 1.0, v70
	v_rcp_f32_e32 v70, v70
	s_nop 0
	v_mul_f32_e32 v70, v83, v70
	v_mul_f32_e32 v82, v82, v70
	v_pk_mul_f32 v[70:71], v[78:79], v[74:75] op_sel_hi:[1,0]
	s_nop 0
	v_mul_f32_e32 v75, 0xbfb8aa3b, v71
	v_exp_f32_e32 v75, v75
	s_nop 0
	v_add_f32_e32 v75, 1.0, v75
	v_rcp_f32_e32 v75, v75
	s_nop 0
	v_mul_f32_e32 v71, v71, v75
	v_mul_f32_e32 v78, v70, v71
	v_mov_b32_e32 v70, v76
	v_mov_b32_e32 v71, v84
	v_pk_mul_f32 v[70:71], v[70:71], v[74:75] op_sel_hi:[1,0]
	v_mov_b32_e32 v84, v77
	v_mul_f32_e32 v75, 0xbfb8aa3b, v71
	v_exp_f32_e32 v75, v75
	s_nop 0
	v_add_f32_e32 v75, 1.0, v75
	v_rcp_f32_e32 v75, v75
	s_nop 0
	v_mul_f32_e32 v71, v71, v75
	v_mul_f32_e32 v76, v70, v71
	v_mov_b32_e32 v70, v72
	v_mov_b32_e32 v71, v80
	v_pk_mul_f32 v[70:71], v[70:71], v[74:75] op_sel_hi:[1,0]
	v_mov_b32_e32 v80, v73
	v_mul_f32_e32 v72, 0xbfb8aa3b, v71
	v_exp_f32_e32 v72, v72
	s_nop 0
	v_add_f32_e32 v72, 1.0, v72
	v_rcp_f32_e32 v72, v72
	s_nop 0
	v_mul_f32_e32 v71, v71, v72
	v_mul_f32_e32 v79, v70, v71
	v_pk_mul_f32 v[70:71], v[84:85], v[74:75] op_sel_hi:[1,0]
	s_nop 0
	v_mul_f32_e32 v72, 0xbfb8aa3b, v71
	v_exp_f32_e32 v72, v72
	s_nop 0
	v_add_f32_e32 v72, 1.0, v72
	v_rcp_f32_e32 v72, v72
	s_nop 0
	v_mul_f32_e32 v71, v71, v72
	v_mul_f32_e32 v72, v70, v71
	v_pk_mul_f32 v[70:71], v[80:81], v[74:75] op_sel_hi:[1,0]
	v_lshl_add_u64 v[74:75], v[86:87], 0, v[122:123]
	v_mul_f32_e32 v73, 0xbfb8aa3b, v71
	v_exp_f32_e32 v73, v73
	s_nop 0
	v_add_f32_e32 v73, 1.0, v73
	v_rcp_f32_e32 v73, v73
	s_nop 0
	v_mul_f32_e32 v71, v71, v73
	v_mul_f32_e32 v73, v70, v71
	v_cvt_pk_bf16_f32 v70, v90, v82
	v_cvt_pk_bf16_f32 v71, v76, v72
	v_cvt_pk_bf16_f32 v72, v88, v78
	v_cvt_pk_bf16_f32 v73, v79, v73
	global_store_dwordx4 v[74:75], v[70:73], off
	s_nop 1
	v_mov_b32_e32 v72, v54
; __device__ __forceinline__ unsigned cvt_pk_bf16(float lo, float hi) { unsigned r; asm volatile("v_cvt_pk_bf16_f32 %0, %1, %2" : "=v"(r) : "v"(lo), "v"(hi)); return r; }
; __device__ __forceinline__ float silu_f(float x) { return x * __builtin_amdgcn_rcpf(1.0f + __builtin_amdgcn_exp2f(-1.4426950408889634f * x)); }
;     __device__ __forceinline__ void operator()(const f32x4 (&acc)[2][2][4][2], const Unit& u, int wr, int wc, int fr, int fq) const {
;     ...
;             for (int m = 0; m < 4; ++m) { bf16_t* rowp = O + (size_t)(row0 + ai * HALF + m * 16) * ldc + col0; const float r = rs[ai][m];
;                 const f32x4 g0 = acc[ai][0][m][0] * r, g1 = acc[ai][0][m][1] * r, u0 = acc[ai][1][m][0] * r, u1 = acc[ai][1][m][1] * r;
;                 f32x4 v0, v1;
; #pragma unroll
;                 for (int i = 0; i < 4; ++i) { v0[i] = silu_f(g0[i]) * u0[i]; v1[i] = silu_f(g1[i]) * u1[i]; }
;                 u32x4 w; w.x = cvt_pk_bf16(v0[0], v0[1]); w.y = cvt_pk_bf16(v0[2], v0[3]); w.z = cvt_pk_bf16(v1[0], v1[1]); w.w = cvt_pk_bf16(v1[2], v1[3]);
;                 *(u32x4*)rowp = w; }
	v_mov_b32_e32 v73, v62
	v_pk_mul_f32 v[72:73], v[72:73], v[66:67] op_sel_hi:[1,0]
	v_mov_b32_e32 v62, v55
	v_mul_f32_e32 v54, 0xbfb8aa3b, v73
	v_exp_f32_e32 v54, v54
	v_add_u32_e32 v70, 0x80, v161
	v_mad_i64_i32 v[70:71], s[22:23], v70, s15, v[152:153]
	v_add_f32_e32 v54, 1.0, v54
	v_rcp_f32_e32 v54, v54
	s_nop 0
	v_mul_f32_e32 v54, v73, v54
	v_mul_f32_e32 v74, v72, v54
	v_mov_b32_e32 v72, v50
	v_mov_b32_e32 v73, v58
	v_pk_mul_f32 v[72:73], v[72:73], v[66:67] op_sel_hi:[1,0]
	v_pk_mul_f32 v[54:55], v[62:63], v[66:67] op_sel_hi:[1,0]
	v_mul_f32_e32 v50, 0xbfb8aa3b, v73
	v_exp_f32_e32 v50, v50
	v_mov_b32_e32 v58, v51
	v_add_f32_e32 v50, 1.0, v50
	v_rcp_f32_e32 v50, v50
	s_nop 0
	v_mul_f32_e32 v50, v73, v50
	v_mul_f32_e32 v72, v72, v50
	v_mul_f32_e32 v50, 0xbfb8aa3b, v55
	v_exp_f32_e32 v50, v50
	s_nop 0
	v_add_f32_e32 v50, 1.0, v50
	v_rcp_f32_e32 v50, v50
	s_nop 0
	v_mul_f32_e32 v50, v55, v50
	v_mul_f32_e32 v62, v54, v50
	v_pk_mul_f32 v[50:51], v[58:59], v[66:67] op_sel_hi:[1,0]
	s_nop 0
	v_mul_f32_e32 v54, 0xbfb8aa3b, v51
	v_exp_f32_e32 v54, v54
	s_nop 0
	v_add_f32_e32 v54, 1.0, v54
	v_rcp_f32_e32 v54, v54
	s_nop 0
	v_mul_f32_e32 v51, v51, v54
	v_mul_f32_e32 v58, v50, v51
	v_mov_b32_e32 v50, v56
	v_mov_b32_e32 v51, v64
	v_pk_mul_f32 v[50:51], v[50:51], v[66:67] op_sel_hi:[1,0]
	v_mov_b32_e32 v64, v57
	v_mul_f32_e32 v54, 0xbfb8aa3b, v51
	v_exp_f32_e32 v54, v54
	s_nop 0
	v_add_f32_e32 v54, 1.0, v54
	v_rcp_f32_e32 v54, v54
	s_nop 0
	v_mul_f32_e32 v51, v51, v54
	v_mul_f32_e32 v56, v50, v51
	v_mov_b32_e32 v50, v52
	v_mov_b32_e32 v51, v60
	v_pk_mul_f32 v[50:51], v[50:51], v[66:67] op_sel_hi:[1,0]
	v_mov_b32_e32 v60, v53
	v_mul_f32_e32 v52, 0xbfb8aa3b, v51
	v_exp_f32_e32 v52, v52
	v_lshl_add_u64 v[54:55], v[70:71], 0, v[122:123]
	v_add_f32_e32 v52, 1.0, v52
	v_rcp_f32_e32 v52, v52
	s_nop 0
	v_mul_f32_e32 v51, v51, v52
	v_mul_f32_e32 v59, v50, v51
	v_pk_mul_f32 v[50:51], v[64:65], v[66:67] op_sel_hi:[1,0]
	s_nop 0
	v_mul_f32_e32 v52, 0xbfb8aa3b, v51
	v_exp_f32_e32 v52, v52
	s_nop 0
	v_add_f32_e32 v52, 1.0, v52
	v_rcp_f32_e32 v52, v52
	s_nop 0
	v_mul_f32_e32 v51, v51, v52
	v_mul_f32_e32 v52, v50, v51
	v_pk_mul_f32 v[50:51], v[60:61], v[66:67] op_sel_hi:[1,0]
	s_nop 0
	v_mul_f32_e32 v53, 0xbfb8aa3b, v51
	v_exp_f32_e32 v53, v53
	s_nop 0
	v_add_f32_e32 v53, 1.0, v53
	v_rcp_f32_e32 v53, v53
	s_nop 0
	v_mul_f32_e32 v51, v51, v53
	v_mul_f32_e32 v53, v50, v51
	v_cvt_pk_bf16_f32 v50, v74, v62
	v_cvt_pk_bf16_f32 v51, v56, v52
	v_cvt_pk_bf16_f32 v52, v72, v58
	v_cvt_pk_bf16_f32 v53, v59, v53
	global_store_dwordx4 v[54:55], v[50:53], off
	s_nop 1
	v_mov_b32_e32 v52, v38
	v_mov_b32_e32 v53, v46
	v_pk_mul_f32 v[52:53], v[52:53], v[66:67] op_sel:[0,1]
	v_mov_b32_e32 v46, v39
	v_mul_f32_e32 v38, 0xbfb8aa3b, v53
	v_exp_f32_e32 v38, v38
	v_add_u32_e32 v50, 0x90, v161
	v_mad_i64_i32 v[50:51], s[22:23], v50, s15, v[152:153]
	v_add_f32_e32 v38, 1.0, v38
	v_rcp_f32_e32 v38, v38
	s_nop 0
	v_mul_f32_e32 v38, v53, v38
	v_mul_f32_e32 v54, v52, v38
	v_mov_b32_e32 v52, v34
	v_mov_b32_e32 v53, v42
	v_pk_mul_f32 v[52:53], v[52:53], v[66:67] op_sel:[0,1]
	v_pk_mul_f32 v[38:39], v[46:47], v[66:67] op_sel:[0,1]
	v_mul_f32_e32 v34, 0xbfb8aa3b, v53
	v_exp_f32_e32 v34, v34
	v_mov_b32_e32 v42, v35
	v_add_f32_e32 v34, 1.0, v34
	v_rcp_f32_e32 v34, v34
	s_nop 0
	v_mul_f32_e32 v34, v53, v34
	v_mul_f32_e32 v52, v52, v34
	v_mul_f32_e32 v34, 0xbfb8aa3b, v39
	v_exp_f32_e32 v34, v34
	s_nop 0
	v_add_f32_e32 v34, 1.0, v34
	v_rcp_f32_e32 v34, v34
	s_nop 0
	v_mul_f32_e32 v34, v39, v34
	v_mul_f32_e32 v46, v38, v34
	v_pk_mul_f32 v[34:35], v[42:43], v[66:67] op_sel:[0,1]
	s_nop 0
	v_mul_f32_e32 v38, 0xbfb8aa3b, v35
	v_exp_f32_e32 v38, v38
	s_nop 0
	v_add_f32_e32 v38, 1.0, v38
	v_rcp_f32_e32 v38, v38
	s_nop 0
	v_mul_f32_e32 v35, v35, v38
	v_mul_f32_e32 v42, v34, v35
	v_mov_b32_e32 v34, v40
	v_mov_b32_e32 v35, v48
	v_pk_mul_f32 v[34:35], v[34:35], v[66:67] op_sel:[0,1]
	v_mov_b32_e32 v48, v41
	v_mul_f32_e32 v38, 0xbfb8aa3b, v35
	v_exp_f32_e32 v38, v38
	s_nop 0
	v_add_f32_e32 v38, 1.0, v38
	v_rcp_f32_e32 v38, v38
	s_nop 0
	v_mul_f32_e32 v35, v35, v38
	v_mul_f32_e32 v40, v34, v35
	v_mov_b32_e32 v34, v36
	v_mov_b32_e32 v35, v44
	v_pk_mul_f32 v[34:35], v[34:35], v[66:67] op_sel:[0,1]
	v_mov_b32_e32 v44, v37
	v_mul_f32_e32 v36, 0xbfb8aa3b, v35
	v_exp_f32_e32 v36, v36
	v_lshl_add_u64 v[38:39], v[50:51], 0, v[122:123]
	v_add_f32_e32 v36, 1.0, v36
	v_rcp_f32_e32 v36, v36
	s_nop 0
	v_mul_f32_e32 v35, v35, v36
	v_mul_f32_e32 v43, v34, v35
	v_pk_mul_f32 v[34:35], v[48:49], v[66:67] op_sel:[0,1]
	s_nop 0
	v_mul_f32_e32 v36, 0xbfb8aa3b, v35
	v_exp_f32_e32 v36, v36
	s_nop 0
	v_add_f32_e32 v36, 1.0, v36
	v_rcp_f32_e32 v36, v36
	s_nop 0
	v_mul_f32_e32 v35, v35, v36
	v_mul_f32_e32 v36, v34, v35
	v_pk_mul_f32 v[34:35], v[44:45], v[66:67] op_sel:[0,1]
	s_nop 0
	v_mul_f32_e32 v37, 0xbfb8aa3b, v35
	v_exp_f32_e32 v37, v37
	s_nop 0
	v_add_f32_e32 v37, 1.0, v37
	v_rcp_f32_e32 v37, v37
	s_nop 0
	v_mul_f32_e32 v35, v35, v37
	v_mul_f32_e32 v37, v34, v35
	v_cvt_pk_bf16_f32 v34, v54, v46
	v_cvt_pk_bf16_f32 v35, v40, v36
	v_cvt_pk_bf16_f32 v36, v52, v42
	v_cvt_pk_bf16_f32 v37, v43, v37
	global_store_dwordx4 v[38:39], v[34:37], off
	s_nop 1
	v_mov_b32_e32 v36, v22
; __device__ __forceinline__ unsigned cvt_pk_bf16(float lo, float hi) { unsigned r; asm volatile("v_cvt_pk_bf16_f32 %0, %1, %2" : "=v"(r) : "v"(lo), "v"(hi)); return r; }
; __device__ __forceinline__ float silu_f(float x) { return x * __builtin_amdgcn_rcpf(1.0f + __builtin_amdgcn_exp2f(-1.4426950408889634f * x)); }
;     __device__ __forceinline__ void operator()(const f32x4 (&acc)[2][2][4][2], const Unit& u, int wr, int wc, int fr, int fq) const {
;     ...
;             for (int m = 0; m < 4; ++m) { bf16_t* rowp = O + (size_t)(row0 + ai * HALF + m * 16) * ldc + col0; const float r = rs[ai][m];
;                 const f32x4 g0 = acc[ai][0][m][0] * r, g1 = acc[ai][0][m][1] * r, u0 = acc[ai][1][m][0] * r, u1 = acc[ai][1][m][1] * r;
;                 f32x4 v0, v1;
; #pragma unroll
;                 for (int i = 0; i < 4; ++i) { v0[i] = silu_f(g0[i]) * u0[i]; v1[i] = silu_f(g1[i]) * u1[i]; }
;                 u32x4 w; w.x = cvt_pk_bf16(v0[0], v0[1]); w.y = cvt_pk_bf16(v0[2], v0[3]); w.z = cvt_pk_bf16(v1[0], v1[1]); w.w = cvt_pk_bf16(v1[2], v1[3]);
;                 *(u32x4*)rowp = w; }
	v_mov_b32_e32 v37, v30
	v_pk_mul_f32 v[36:37], v[36:37], v[68:69] op_sel_hi:[1,0]
	v_mov_b32_e32 v30, v23
	v_mul_f32_e32 v22, 0xbfb8aa3b, v37
	v_exp_f32_e32 v22, v22
	v_add_u32_e32 v34, 0xa0, v161
	v_mad_i64_i32 v[34:35], s[22:23], v34, s15, v[152:153]
	v_add_f32_e32 v22, 1.0, v22
	v_rcp_f32_e32 v22, v22
	s_nop 0
	v_mul_f32_e32 v22, v37, v22
	v_mul_f32_e32 v38, v36, v22
	v_mov_b32_e32 v36, v18
	v_mov_b32_e32 v37, v26
	v_pk_mul_f32 v[36:37], v[36:37], v[68:69] op_sel_hi:[1,0]
	v_pk_mul_f32 v[22:23], v[30:31], v[68:69] op_sel_hi:[1,0]
	v_mul_f32_e32 v18, 0xbfb8aa3b, v37
	v_exp_f32_e32 v18, v18
	v_mov_b32_e32 v26, v19
	v_add_f32_e32 v18, 1.0, v18
	v_rcp_f32_e32 v18, v18
	s_nop 0
	v_mul_f32_e32 v18, v37, v18
	v_mul_f32_e32 v36, v36, v18
	v_mul_f32_e32 v18, 0xbfb8aa3b, v23
	v_exp_f32_e32 v18, v18
	s_nop 0
	v_add_f32_e32 v18, 1.0, v18
	v_rcp_f32_e32 v18, v18
	s_nop 0
	v_mul_f32_e32 v18, v23, v18
	v_mul_f32_e32 v30, v22, v18
	v_pk_mul_f32 v[18:19], v[26:27], v[68:69] op_sel_hi:[1,0]
	s_nop 0
	v_mul_f32_e32 v22, 0xbfb8aa3b, v19
	v_exp_f32_e32 v22, v22
	s_nop 0
	v_add_f32_e32 v22, 1.0, v22
	v_rcp_f32_e32 v22, v22
	s_nop 0
	v_mul_f32_e32 v19, v19, v22
	v_mul_f32_e32 v26, v18, v19
	v_mov_b32_e32 v18, v24
	v_mov_b32_e32 v19, v32
	v_pk_mul_f32 v[18:19], v[18:19], v[68:69] op_sel_hi:[1,0]
	v_mov_b32_e32 v32, v25
	v_mul_f32_e32 v22, 0xbfb8aa3b, v19
	v_exp_f32_e32 v22, v22
	s_nop 0
	v_add_f32_e32 v22, 1.0, v22
	v_rcp_f32_e32 v22, v22
	s_nop 0
	v_mul_f32_e32 v19, v19, v22
	v_mul_f32_e32 v24, v18, v19
	v_mov_b32_e32 v18, v20
	v_mov_b32_e32 v19, v28
	v_pk_mul_f32 v[18:19], v[18:19], v[68:69] op_sel_hi:[1,0]
	v_mov_b32_e32 v28, v21
	v_mul_f32_e32 v20, 0xbfb8aa3b, v19
	v_exp_f32_e32 v20, v20
	v_lshl_add_u64 v[22:23], v[34:35], 0, v[122:123]
	v_add_f32_e32 v20, 1.0, v20
	v_rcp_f32_e32 v20, v20
	s_nop 0
	v_mul_f32_e32 v19, v19, v20
	v_mul_f32_e32 v27, v18, v19
	v_pk_mul_f32 v[18:19], v[32:33], v[68:69] op_sel_hi:[1,0]
	s_nop 0
	v_mul_f32_e32 v20, 0xbfb8aa3b, v19
	v_exp_f32_e32 v20, v20
	s_nop 0
	v_add_f32_e32 v20, 1.0, v20
	v_rcp_f32_e32 v20, v20
	s_nop 0
	v_mul_f32_e32 v19, v19, v20
	v_mul_f32_e32 v20, v18, v19
	v_pk_mul_f32 v[18:19], v[28:29], v[68:69] op_sel_hi:[1,0]
	s_nop 0
	v_mul_f32_e32 v21, 0xbfb8aa3b, v19
	v_exp_f32_e32 v21, v21
	s_nop 0
	v_add_f32_e32 v21, 1.0, v21
	v_rcp_f32_e32 v21, v21
	s_nop 0
	v_mul_f32_e32 v19, v19, v21
	v_mul_f32_e32 v21, v18, v19
	v_cvt_pk_bf16_f32 v18, v38, v30
	v_cvt_pk_bf16_f32 v19, v24, v20
	v_cvt_pk_bf16_f32 v20, v36, v26
	v_cvt_pk_bf16_f32 v21, v27, v21
	global_store_dwordx4 v[22:23], v[18:21], off
	s_nop 1
	v_mov_b32_e32 v20, v6
	v_mov_b32_e32 v21, v14
	v_mov_b32_e32 v6, v69
	v_pk_mul_f32 v[20:21], v[20:21], v[6:7] op_sel_hi:[1,0]
	v_add_u32_e32 v18, 0xb0, v161
	v_mul_f32_e32 v14, 0xbfb8aa3b, v21
	v_exp_f32_e32 v14, v14
	v_mad_i64_i32 v[18:19], s[22:23], v18, s15, v[152:153]
	s_mov_b64 s[22:23], -1
	v_add_f32_e32 v14, 1.0, v14
	v_rcp_f32_e32 v14, v14
	s_nop 0
	v_mul_f32_e32 v14, v21, v14
	v_mul_f32_e32 v22, v20, v14
	v_mov_b32_e32 v20, v2
	v_mov_b32_e32 v21, v10
	v_pk_mul_f32 v[20:21], v[20:21], v[6:7] op_sel_hi:[1,0]
	v_mov_b32_e32 v14, v7
	v_mul_f32_e32 v2, 0xbfb8aa3b, v21
	v_exp_f32_e32 v2, v2
	v_pk_mul_f32 v[14:15], v[14:15], v[6:7] op_sel_hi:[1,0]
	v_mov_b32_e32 v10, v3
	v_add_f32_e32 v2, 1.0, v2
	v_rcp_f32_e32 v2, v2
	s_nop 0
	v_mul_f32_e32 v2, v21, v2
	v_mul_f32_e32 v20, v20, v2
	v_mul_f32_e32 v2, 0xbfb8aa3b, v15
	v_exp_f32_e32 v2, v2
	s_nop 0
	v_add_f32_e32 v2, 1.0, v2
	v_rcp_f32_e32 v2, v2
	s_nop 0
	v_mul_f32_e32 v2, v15, v2
	v_mul_f32_e32 v14, v14, v2
	v_pk_mul_f32 v[2:3], v[10:11], v[6:7] op_sel_hi:[1,0]
	s_nop 0
	v_mul_f32_e32 v7, 0xbfb8aa3b, v3
	v_exp_f32_e32 v7, v7
	s_nop 0
	v_add_f32_e32 v7, 1.0, v7
	v_rcp_f32_e32 v7, v7
	s_nop 0
	v_mul_f32_e32 v3, v3, v7
	v_mul_f32_e32 v10, v2, v3
	v_mov_b32_e32 v2, v8
	v_mov_b32_e32 v3, v16
	v_pk_mul_f32 v[2:3], v[2:3], v[6:7] op_sel_hi:[1,0]
	v_mov_b32_e32 v16, v9
	v_mul_f32_e32 v7, 0xbfb8aa3b, v3
	v_exp_f32_e32 v7, v7
	s_nop 0
	v_add_f32_e32 v7, 1.0, v7
	v_rcp_f32_e32 v7, v7
	s_nop 0
	v_mul_f32_e32 v3, v3, v7
	v_mul_f32_e32 v8, v2, v3
	v_mov_b32_e32 v2, v4
	v_mov_b32_e32 v3, v12
	v_pk_mul_f32 v[2:3], v[2:3], v[6:7] op_sel_hi:[1,0]
	v_mov_b32_e32 v12, v5
	v_mul_f32_e32 v4, 0xbfb8aa3b, v3
	v_exp_f32_e32 v4, v4
	s_nop 0
	v_add_f32_e32 v4, 1.0, v4
	v_rcp_f32_e32 v4, v4
	s_nop 0
	v_mul_f32_e32 v3, v3, v4
	v_mul_f32_e32 v11, v2, v3
	v_pk_mul_f32 v[2:3], v[16:17], v[6:7] op_sel_hi:[1,0]
	s_nop 0
	v_mul_f32_e32 v4, 0xbfb8aa3b, v3
	v_exp_f32_e32 v4, v4
	s_nop 0
	v_add_f32_e32 v4, 1.0, v4
	v_rcp_f32_e32 v4, v4
	s_nop 0
	v_mul_f32_e32 v3, v3, v4
	v_mul_f32_e32 v4, v2, v3
	v_pk_mul_f32 v[2:3], v[12:13], v[6:7] op_sel_hi:[1,0]
	v_lshl_add_u64 v[6:7], v[18:19], 0, v[122:123]
	v_mul_f32_e32 v5, 0xbfb8aa3b, v3
	v_exp_f32_e32 v5, v5
	s_nop 0
	v_add_f32_e32 v5, 1.0, v5
	v_rcp_f32_e32 v5, v5
	s_nop 0
	v_mul_f32_e32 v3, v3, v5
	v_mul_f32_e32 v5, v2, v3
	v_cvt_pk_bf16_f32 v2, v22, v14
	v_cvt_pk_bf16_f32 v3, v8, v4
	v_cvt_pk_bf16_f32 v4, v20, v10
	v_cvt_pk_bf16_f32 v5, v11, v5
	global_store_dwordx4 v[6:7], v[2:5], off
	s_cbranch_vccnz .LBB0_1245
	s_andn2_b64 vcc, exec, s[6:7]
	s_cbranch_vccnz .LBB0_1244
	s_barrier
	s_branch .LBB0_1244
